# attention: K/V LDS-DMA issue spread through the exp/PV block (saddr form, offsets hoisted per item) instead of one burst; band+win
# speedup vs baseline: 1.0044x; 1.0044x over previous
; #define PG8_STAGE(bufoff, gbase, voff) do { _Pragma("unroll") for (int _i = 0; _i < 2; ++_i) \
;         __builtin_amdgcn_global_load_lds((const unsigned*)((const char*)(gbase) + (voff)[_i]), (LAS unsigned*)(lds + (bufoff) + ldsw + _i * 8192), 16, 0, 0); } while (0)
; #define PG8_LDA(dst, b, h) do { _Pragma("unroll") for (int m = 0; m < 4; ++m) _Pragma("unroll") for (int k = 0; k < 2; ++k) dst[m][k] = *(const LAS bf16x8*)(lds + PG8_SA(b, h) + aoff + m * 2048 + k * 1024); } while (0)
; #define PG8_LDB(dst, b, h) do { _Pragma("unroll") for (int n = 0; n < 2; ++n) _Pragma("unroll") for (int k = 0; k < 2; ++k) dst[n][k] = *(const LAS bf16x8*)(lds + PG8_SB(b, h) + boff + n * 2048 + k * 1024); } while (0)
; #define PG8_MMA(ai, bj, At, Bt) do { __builtin_amdgcn_s_setprio(1); _Pragma("unroll") for (int m = 0; m < 4; ++m) _Pragma("unroll") for (int n = 0; n < 2; ++n) _Pragma("unroll") for (int k = 0; k < 2; ++k) \
;         acc[ai][bj][m][n] = __builtin_amdgcn_mfma_f32_16x16x32_bf16(Bt[n][k], At[m][k], acc[ai][bj][m][n], 0, 0, 0); __builtin_amdgcn_s_setprio(0); } while (0)
; #define PG8_WAIT_V(n) asm volatile("s_waitcnt vmcnt(" #n ")" ::: "memory")
; #define PG8_WAIT_L(n) asm volatile("s_waitcnt lgkmcnt(" #n ")" ::: "memory")
; #define PG8_BAR __builtin_amdgcn_s_barrier()
; template <class Epi, int AC0, int BC0, int NT0, int AC1, int BC1, int NT1>
; __device__ __forceinline__ void gemm_phase(LAS unsigned char* lds, const Gemm g, const StaticOrder& S, const Epi& E, int tid) {
;     ...
;         for (int t = 0; t < nt; t += 2) {
;             const bool last = (t == nt - 2);
;             const char* a1 = cA + (size_t)(t + 1) * kstep;
;             const char* a2 = last ? nA : cA + (size_t)(t + 2) * kstep; const char* b2 = last ? nB : cB + (size_t)(t + 2) * kstep;
;             const char* a3 = a2 + kstep; const char* b3 = b2 + kstep;
;             PG8_LDB(B0, 0, 0); PG8_LDB(B1, 0, 1); PG8_SCHED; PG8_LDA(At, 0, 0); PG8_STAGE(PG8_SA(1, 1), a1 + hstepA, voffA);
;             PG8_WAIT_V(8); PG8_WAIT_L(0); PG8_BAR; PG8_MMA(0, 0, At, B0); PG8_MMA(0, 1, At, B1); PG8_BAR; PG8_SCHED;
;             PG8_LDA(At, 0, 1); PG8_STAGE(PG8_SB(0, 0), b2, voffB); PG8_STAGE(PG8_SB(0, 1), b2 + hstepB, voffB); PG8_STAGE(PG8_SA(0, 0), a2, voffA);
;             PG8_WAIT_V(8); PG8_WAIT_L(0); PG8_BAR; PG8_MMA(1, 0, At, B0); PG8_MMA(1, 1, At, B1); PG8_BAR; PG8_SCHED;
.LBB0_124:
	ds_read_b128 v[26:29], v192
	ds_read_b128 v[30:33], v192 offset:1024
	ds_read_b128 v[42:45], v192 offset:2048
	ds_read_b128 v[46:49], v192 offset:3072
	ds_read_b128 v[146:149], v193
	ds_read_b128 v[150:153], v193 offset:1024
	ds_read_b128 v[154:157], v193 offset:2048
	ds_read_b128 v[158:161], v193 offset:3072
	s_add_u32 s6, s0, 0xfffc0080
	s_addc_u32 s7, s1, -1
	s_cmp_eq_u32 s27, 12
	s_cselect_b32 s13, s3, s7
	s_cselect_b32 s12, s9, s6
	s_cselect_b32 s7, s11, s22
	s_cselect_b32 s6, s15, s16
	v_lshl_add_u64 v[186:187], s[0:1], 0, v[178:179]
	s_add_i32 m0, s95, 0xc000
	ds_read_b128 v[198:201], v194
	ds_read_b128 v[202:205], v194 offset:1024
	ds_read_b128 v[206:209], v194 offset:2048
	ds_read_b128 v[210:213], v194 offset:3072
	ds_read_b128 v[214:217], v194 offset:4096
	ds_read_b128 v[218:221], v194 offset:5120
	ds_read_b128 v[226:229], v194 offset:6144
	ds_read_b128 v[230:233], v194 offset:7168
	global_load_lds_dwordx4 v[186:187], off
	v_lshl_add_u64 v[186:187], s[0:1], 0, v[180:181]
	s_add_i32 m0, s95, 0xe000
	s_nop 0
	global_load_lds_dwordx4 v[186:187], off
	s_waitcnt vmcnt(8)
	s_waitcnt lgkmcnt(0)
	s_barrier
	s_setprio 1
	s_waitcnt lgkmcnt(0)
	v_mfma_f32_16x16x32_bf16 v[142:145], v[26:29], v[198:201], v[142:145]
	v_mfma_f32_16x16x32_bf16 v[138:141], v[42:45], v[198:201], v[138:141]
	v_mfma_f32_16x16x32_bf16 v[126:129], v[26:29], v[206:209], v[126:129]
	v_mfma_f32_16x16x32_bf16 v[122:125], v[42:45], v[206:209], v[122:125]
	v_mfma_f32_16x16x32_bf16 v[110:113], v[26:29], v[214:217], v[110:113]
	v_mfma_f32_16x16x32_bf16 v[106:109], v[42:45], v[214:217], v[106:109]
	v_mfma_f32_16x16x32_bf16 v[94:97], v[26:29], v[226:229], v[94:97]
	v_mfma_f32_16x16x32_bf16 v[90:93], v[42:45], v[226:229], v[90:93]
	v_mfma_f32_16x16x32_bf16 v[142:145], v[30:33], v[202:205], v[142:145]
	v_mfma_f32_16x16x32_bf16 v[138:141], v[46:49], v[202:205], v[138:141]
	v_mfma_f32_16x16x32_bf16 v[126:129], v[30:33], v[210:213], v[126:129]
	v_mfma_f32_16x16x32_bf16 v[122:125], v[46:49], v[210:213], v[122:125]
	v_mfma_f32_16x16x32_bf16 v[110:113], v[30:33], v[218:221], v[110:113]
	v_mfma_f32_16x16x32_bf16 v[106:109], v[46:49], v[218:221], v[106:109]
	v_mfma_f32_16x16x32_bf16 v[94:97], v[30:33], v[230:233], v[94:97]
	v_mfma_f32_16x16x32_bf16 v[90:93], v[46:49], v[230:233], v[90:93]
	s_setprio 0
	s_setprio 1
	v_mfma_f32_16x16x32_bf16 v[134:137], v[146:149], v[198:201], v[134:137]
	v_mfma_f32_16x16x32_bf16 v[130:133], v[154:157], v[198:201], v[130:133]
	v_mfma_f32_16x16x32_bf16 v[118:121], v[146:149], v[206:209], v[118:121]
	v_mfma_f32_16x16x32_bf16 v[114:117], v[154:157], v[206:209], v[114:117]
	v_mfma_f32_16x16x32_bf16 v[102:105], v[146:149], v[214:217], v[102:105]
	v_mfma_f32_16x16x32_bf16 v[98:101], v[154:157], v[214:217], v[98:101]
	v_mfma_f32_16x16x32_bf16 v[86:89], v[146:149], v[226:229], v[86:89]
	v_mfma_f32_16x16x32_bf16 v[82:85], v[154:157], v[226:229], v[82:85]
	v_mfma_f32_16x16x32_bf16 v[134:137], v[150:153], v[202:205], v[134:137]
	v_mfma_f32_16x16x32_bf16 v[130:133], v[158:161], v[202:205], v[130:133]
	v_mfma_f32_16x16x32_bf16 v[118:121], v[150:153], v[210:213], v[118:121]
	v_mfma_f32_16x16x32_bf16 v[114:117], v[158:161], v[210:213], v[114:117]
	v_mfma_f32_16x16x32_bf16 v[102:105], v[150:153], v[218:221], v[102:105]
	v_mfma_f32_16x16x32_bf16 v[98:101], v[158:161], v[218:221], v[98:101]
	v_mfma_f32_16x16x32_bf16 v[86:89], v[150:153], v[230:233], v[86:89]
	v_mfma_f32_16x16x32_bf16 v[82:85], v[158:161], v[230:233], v[82:85]
	s_setprio 0
	s_barrier
	s_add_i32 s29, s94, s47
	v_lshl_add_u64 v[186:187], s[6:7], 0, v[166:167]
	s_mov_b32 m0, s29
	ds_read_b128 v[198:201], v194 offset:16384
	ds_read_b128 v[202:205], v194 offset:17408
	ds_read_b128 v[206:209], v194 offset:18432
	ds_read_b128 v[210:213], v194 offset:19456
	ds_read_b128 v[214:217], v194 offset:20480
	ds_read_b128 v[218:221], v194 offset:21504
	ds_read_b128 v[226:229], v194 offset:22528
	ds_read_b128 v[230:233], v194 offset:23552
	global_load_lds_dwordx4 v[186:187], off
	s_add_i32 m0, s29, 0x2000
	s_add_u32 s36, s6, 0x40000
	v_lshl_add_u64 v[222:223], s[6:7], 0, v[170:171]
	s_addc_u32 s37, s7, 0
	s_add_i32 s29, s18, s47
	global_load_lds_dwordx4 v[222:223], off
	v_lshl_add_u64 v[234:235], s[36:37], 0, v[166:167]
	s_mov_b32 m0, s29
	v_lshl_add_u64 v[236:237], s[12:13], 0, v[168:169]
	global_load_lds_dwordx4 v[234:235], off
	v_lshl_add_u64 v[234:235], s[36:37], 0, v[170:171]
	s_add_i32 m0, s29, 0x2000
	s_nop 0
	global_load_lds_dwordx4 v[234:235], off
	v_lshl_add_u64 v[234:235], s[12:13], 0, v[164:165]
	s_mov_b32 m0, s95
	s_nop 0
	global_load_lds_dwordx4 v[234:235], off
	s_mov_b32 m0, s96
	s_nop 0
	global_load_lds_dwordx4 v[236:237], off
	s_waitcnt vmcnt(8)
	s_waitcnt lgkmcnt(0)
	s_barrier
; #define PG8_STAGE(bufoff, gbase, voff) do { _Pragma("unroll") for (int _i = 0; _i < 2; ++_i) \
;         __builtin_amdgcn_global_load_lds((const unsigned*)((const char*)(gbase) + (voff)[_i]), (LAS unsigned*)(lds + (bufoff) + ldsw + _i * 8192), 16, 0, 0); } while (0)
; #define PG8_LDA(dst, b, h) do { _Pragma("unroll") for (int m = 0; m < 4; ++m) _Pragma("unroll") for (int k = 0; k < 2; ++k) dst[m][k] = *(const LAS bf16x8*)(lds + PG8_SA(b, h) + aoff + m * 2048 + k * 1024); } while (0)
; #define PG8_LDB(dst, b, h) do { _Pragma("unroll") for (int n = 0; n < 2; ++n) _Pragma("unroll") for (int k = 0; k < 2; ++k) dst[n][k] = *(const LAS bf16x8*)(lds + PG8_SB(b, h) + boff + n * 2048 + k * 1024); } while (0)
; #define PG8_MMA(ai, bj, At, Bt) do { __builtin_amdgcn_s_setprio(1); _Pragma("unroll") for (int m = 0; m < 4; ++m) _Pragma("unroll") for (int n = 0; n < 2; ++n) _Pragma("unroll") for (int k = 0; k < 2; ++k) \
;         acc[ai][bj][m][n] = __builtin_amdgcn_mfma_f32_16x16x32_bf16(Bt[n][k], At[m][k], acc[ai][bj][m][n], 0, 0, 0); __builtin_amdgcn_s_setprio(0); } while (0)
; #define PG8_WAIT_V(n) asm volatile("s_waitcnt vmcnt(" #n ")" ::: "memory")
; #define PG8_WAIT_L(n) asm volatile("s_waitcnt lgkmcnt(" #n ")" ::: "memory")
; #define PG8_BAR __builtin_amdgcn_s_barrier()
; #define PG8_SCHED __builtin_amdgcn_sched_barrier(0)
; template <class Epi, int AC0, int BC0, int NT0, int AC1, int BC1, int NT1>
; __device__ __forceinline__ void gemm_phase(LAS unsigned char* lds, const Gemm g, const StaticOrder& S, const Epi& E, int tid) {
;     ...
;             PG8_WAIT_V(8); PG8_WAIT_L(0); PG8_BAR; PG8_MMA(1, 0, At, B0); PG8_MMA(1, 1, At, B1); PG8_BAR; PG8_SCHED;
;             PG8_LDB(B0, 1, 0); PG8_LDB(B1, 1, 1); PG8_SCHED; PG8_LDA(At, 1, 0); PG8_STAGE(PG8_SA(0, 1), a2 + hstepA, voffA);
;             PG8_WAIT_V(8); PG8_WAIT_L(0); PG8_BAR; PG8_MMA(0, 0, At, B0); PG8_MMA(0, 1, At, B1); PG8_BAR; PG8_SCHED;
	s_setprio 1
	s_waitcnt lgkmcnt(0)
	v_mfma_f32_16x16x32_bf16 v[78:81], v[26:29], v[198:201], v[78:81]
	v_mfma_f32_16x16x32_bf16 v[74:77], v[42:45], v[198:201], v[74:77]
	v_mfma_f32_16x16x32_bf16 v[62:65], v[26:29], v[206:209], v[62:65]
	v_mfma_f32_16x16x32_bf16 v[58:61], v[42:45], v[206:209], v[58:61]
	v_mfma_f32_16x16x32_bf16 v[38:41], v[26:29], v[214:217], v[38:41]
	v_mfma_f32_16x16x32_bf16 v[34:37], v[42:45], v[214:217], v[34:37]
	v_mfma_f32_16x16x32_bf16 v[14:17], v[26:29], v[226:229], v[14:17]
	v_mfma_f32_16x16x32_bf16 v[10:13], v[42:45], v[226:229], v[10:13]
	v_mfma_f32_16x16x32_bf16 v[78:81], v[30:33], v[202:205], v[78:81]
	v_mfma_f32_16x16x32_bf16 v[74:77], v[46:49], v[202:205], v[74:77]
	v_mfma_f32_16x16x32_bf16 v[62:65], v[30:33], v[210:213], v[62:65]
	v_mfma_f32_16x16x32_bf16 v[58:61], v[46:49], v[210:213], v[58:61]
	v_mfma_f32_16x16x32_bf16 v[38:41], v[30:33], v[218:221], v[38:41]
	v_mfma_f32_16x16x32_bf16 v[34:37], v[46:49], v[218:221], v[34:37]
	v_mfma_f32_16x16x32_bf16 v[14:17], v[30:33], v[230:233], v[14:17]
	v_mfma_f32_16x16x32_bf16 v[10:13], v[46:49], v[230:233], v[10:13]
	s_setprio 0
	s_setprio 1
	v_mfma_f32_16x16x32_bf16 v[22:25], v[146:149], v[214:217], v[22:25]
	v_mfma_f32_16x16x32_bf16 v[18:21], v[154:157], v[214:217], v[18:21]
	v_mfma_f32_16x16x32_bf16 v[6:9], v[146:149], v[226:229], v[6:9]
	v_mfma_f32_16x16x32_bf16 v[2:5], v[154:157], v[226:229], v[2:5]
	v_mfma_f32_16x16x32_bf16 v[26:29], v[146:149], v[198:201], v[70:73]
	v_mfma_f32_16x16x32_bf16 v[30:33], v[154:157], v[198:201], v[66:69]
	v_mfma_f32_16x16x32_bf16 v[42:45], v[146:149], v[206:209], v[54:57]
	v_mfma_f32_16x16x32_bf16 v[46:49], v[154:157], v[206:209], v[50:53]
	v_mfma_f32_16x16x32_bf16 v[22:25], v[150:153], v[218:221], v[22:25]
	v_mfma_f32_16x16x32_bf16 v[18:21], v[158:161], v[218:221], v[18:21]
	v_mfma_f32_16x16x32_bf16 v[6:9], v[150:153], v[230:233], v[6:9]
	v_mfma_f32_16x16x32_bf16 v[2:5], v[158:161], v[230:233], v[2:5]
	v_mfma_f32_16x16x32_bf16 v[26:29], v[150:153], v[202:205], v[26:29]
	v_mfma_f32_16x16x32_bf16 v[30:33], v[158:161], v[202:205], v[30:33]
	v_mfma_f32_16x16x32_bf16 v[42:45], v[150:153], v[210:213], v[42:45]
	v_mfma_f32_16x16x32_bf16 v[46:49], v[158:161], v[210:213], v[46:49]
	s_setprio 0
	s_barrier
	s_add_i32 s29, 0, 0x18000
	s_add_i32 s33, 0, 0x1c000
	v_add_u32_e32 v70, s29, v188
	v_add_u32_e32 v158, s33, v188
	ds_read_b128 v[50:53], v70
	ds_read_b128 v[54:57], v70 offset:1024
	ds_read_b128 v[66:69], v70 offset:2048
	ds_read_b128 v[70:73], v70 offset:3072
	ds_read_b128 v[146:149], v158
	ds_read_b128 v[150:153], v158 offset:1024
	ds_read_b128 v[154:157], v158 offset:2048
	ds_read_b128 v[158:161], v158 offset:3072
	s_add_u32 s12, s12, 0x40000
	s_addc_u32 s13, s13, 0
	s_mov_b32 m0, s97
	v_lshl_add_u64 v[238:239], s[12:13], 0, v[164:165]
	ds_read_b128 v[198:201], v194 offset:32768
	ds_read_b128 v[202:205], v194 offset:33792
	ds_read_b128 v[206:209], v194 offset:34816
	ds_read_b128 v[210:213], v194 offset:35840
	ds_read_b128 v[214:217], v194 offset:36864
	ds_read_b128 v[218:221], v194 offset:37888
	ds_read_b128 v[226:229], v194 offset:38912
	ds_read_b128 v[230:233], v194 offset:39936
	global_load_lds_dwordx4 v[238:239], off
	v_lshl_add_u64 v[238:239], s[12:13], 0, v[168:169]
	s_mov_b32 m0, s93
	s_nop 0
	global_load_lds_dwordx4 v[238:239], off
	s_waitcnt vmcnt(8)
	s_waitcnt lgkmcnt(0)
	s_barrier
	s_setprio 1
	s_waitcnt lgkmcnt(0)
	v_mfma_f32_16x16x32_bf16 v[142:145], v[50:53], v[198:201], v[142:145]
	v_mfma_f32_16x16x32_bf16 v[138:141], v[66:69], v[198:201], v[138:141]
	v_mfma_f32_16x16x32_bf16 v[126:129], v[50:53], v[206:209], v[126:129]
	v_mfma_f32_16x16x32_bf16 v[122:125], v[66:69], v[206:209], v[122:125]
	v_mfma_f32_16x16x32_bf16 v[110:113], v[50:53], v[214:217], v[110:113]
	v_mfma_f32_16x16x32_bf16 v[106:109], v[66:69], v[214:217], v[106:109]
	v_mfma_f32_16x16x32_bf16 v[94:97], v[50:53], v[226:229], v[94:97]
	v_mfma_f32_16x16x32_bf16 v[90:93], v[66:69], v[226:229], v[90:93]
	v_mfma_f32_16x16x32_bf16 v[142:145], v[54:57], v[202:205], v[142:145]
	v_mfma_f32_16x16x32_bf16 v[138:141], v[70:73], v[202:205], v[138:141]
	v_mfma_f32_16x16x32_bf16 v[126:129], v[54:57], v[210:213], v[126:129]
	v_mfma_f32_16x16x32_bf16 v[122:125], v[70:73], v[210:213], v[122:125]
	v_mfma_f32_16x16x32_bf16 v[110:113], v[54:57], v[218:221], v[110:113]
	v_mfma_f32_16x16x32_bf16 v[106:109], v[70:73], v[218:221], v[106:109]
	v_mfma_f32_16x16x32_bf16 v[94:97], v[54:57], v[230:233], v[94:97]
	v_mfma_f32_16x16x32_bf16 v[90:93], v[70:73], v[230:233], v[90:93]
	s_setprio 0
	s_setprio 1
	v_mfma_f32_16x16x32_bf16 v[134:137], v[146:149], v[198:201], v[134:137]
	v_mfma_f32_16x16x32_bf16 v[130:133], v[154:157], v[198:201], v[130:133]
	v_mfma_f32_16x16x32_bf16 v[118:121], v[146:149], v[206:209], v[118:121]
	v_mfma_f32_16x16x32_bf16 v[114:117], v[154:157], v[206:209], v[114:117]
	v_mfma_f32_16x16x32_bf16 v[102:105], v[146:149], v[214:217], v[102:105]
	v_mfma_f32_16x16x32_bf16 v[98:101], v[154:157], v[214:217], v[98:101]
	v_mfma_f32_16x16x32_bf16 v[86:89], v[146:149], v[226:229], v[86:89]
	v_mfma_f32_16x16x32_bf16 v[82:85], v[154:157], v[226:229], v[82:85]
	v_mfma_f32_16x16x32_bf16 v[134:137], v[150:153], v[202:205], v[134:137]
	v_mfma_f32_16x16x32_bf16 v[130:133], v[158:161], v[202:205], v[130:133]
	v_mfma_f32_16x16x32_bf16 v[118:121], v[150:153], v[210:213], v[118:121]
	v_mfma_f32_16x16x32_bf16 v[114:117], v[158:161], v[210:213], v[114:117]
	v_mfma_f32_16x16x32_bf16 v[102:105], v[150:153], v[218:221], v[102:105]
	v_mfma_f32_16x16x32_bf16 v[98:101], v[158:161], v[218:221], v[98:101]
	v_mfma_f32_16x16x32_bf16 v[86:89], v[150:153], v[230:233], v[86:89]
	v_mfma_f32_16x16x32_bf16 v[82:85], v[158:161], v[230:233], v[82:85]
	s_setprio 0
	s_barrier
; #define PG8_STAGE(bufoff, gbase, voff) do { _Pragma("unroll") for (int _i = 0; _i < 2; ++_i) \
;         __builtin_amdgcn_global_load_lds((const unsigned*)((const char*)(gbase) + (voff)[_i]), (LAS unsigned*)(lds + (bufoff) + ldsw + _i * 8192), 16, 0, 0); } while (0)
; #define PG8_LDA(dst, b, h) do { _Pragma("unroll") for (int m = 0; m < 4; ++m) _Pragma("unroll") for (int k = 0; k < 2; ++k) dst[m][k] = *(const LAS bf16x8*)(lds + PG8_SA(b, h) + aoff + m * 2048 + k * 1024); } while (0)
; #define PG8_MMA(ai, bj, At, Bt) do { __builtin_amdgcn_s_setprio(1); _Pragma("unroll") for (int m = 0; m < 4; ++m) _Pragma("unroll") for (int n = 0; n < 2; ++n) _Pragma("unroll") for (int k = 0; k < 2; ++k) \
;         acc[ai][bj][m][n] = __builtin_amdgcn_mfma_f32_16x16x32_bf16(Bt[n][k], At[m][k], acc[ai][bj][m][n], 0, 0, 0); __builtin_amdgcn_s_setprio(0); } while (0)
; #define PG8_WAIT_V(n) asm volatile("s_waitcnt vmcnt(" #n ")" ::: "memory")
; #define PG8_WAIT_L(n) asm volatile("s_waitcnt lgkmcnt(" #n ")" ::: "memory")
; #define PG8_BAR __builtin_amdgcn_s_barrier()
; #define PG8_SCHED __builtin_amdgcn_sched_barrier(0)
; template <class Epi, int AC0, int BC0, int NT0, int AC1, int BC1, int NT1>
; __device__ __forceinline__ void gemm_phase(LAS unsigned char* lds, const Gemm g, const StaticOrder& S, const Epi& E, int tid) {
;     ...
;             PG8_LDA(At, 1, 1); PG8_STAGE(PG8_SB(1, 0), b3, voffB); PG8_STAGE(PG8_SB(1, 1), b3 + hstepB, voffB); PG8_STAGE(PG8_SA(1, 0), a3, voffA);
;             PG8_WAIT_V(8); PG8_WAIT_L(0); PG8_BAR; PG8_MMA(1, 0, At, B0); PG8_MMA(1, 1, At, B1); PG8_BAR; PG8_SCHED;
;         }
;         if (wr == 0) PG8_BAR;
	s_add_i32 s12, s29, s47
	v_lshl_add_u64 v[186:187], v[186:187], 0, s[20:21]
	s_mov_b32 m0, s12
	ds_read_b128 v[198:201], v194 offset:49152
	ds_read_b128 v[202:205], v194 offset:50176
	ds_read_b128 v[206:209], v194 offset:51200
	ds_read_b128 v[210:213], v194 offset:52224
	ds_read_b128 v[214:217], v194 offset:53248
	ds_read_b128 v[218:221], v194 offset:54272
	ds_read_b128 v[226:229], v194 offset:55296
	ds_read_b128 v[230:233], v194 offset:56320
	global_load_lds_dwordx4 v[186:187], off
	s_add_i32 m0, s12, 0x2000
	s_add_u32 s6, s6, 0x40080
	v_lshl_add_u64 v[186:187], v[222:223], 0, s[20:21]
	s_addc_u32 s7, s7, 0
	s_add_i32 s12, s33, s47
	global_load_lds_dwordx4 v[186:187], off
	v_lshl_add_u64 v[186:187], s[6:7], 0, v[166:167]
	s_mov_b32 m0, s12
	s_nop 0
	global_load_lds_dwordx4 v[186:187], off
	v_lshl_add_u64 v[186:187], s[6:7], 0, v[170:171]
	s_add_i32 m0, s12, 0x2000
	s_nop 0
	global_load_lds_dwordx4 v[186:187], off
	v_lshl_add_u64 v[186:187], v[234:235], 0, s[20:21]
	s_mov_b32 m0, s19
	s_nop 0
	global_load_lds_dwordx4 v[186:187], off
	v_lshl_add_u64 v[186:187], v[236:237], 0, s[20:21]
	s_mov_b32 m0, s46
	s_nop 0
	global_load_lds_dwordx4 v[186:187], off
	s_waitcnt vmcnt(8)
	s_waitcnt lgkmcnt(0)
	s_barrier
	s_setprio 1
	s_waitcnt lgkmcnt(0)
	v_mfma_f32_16x16x32_bf16 v[78:81], v[50:53], v[198:201], v[78:81]
	v_mfma_f32_16x16x32_bf16 v[74:77], v[66:69], v[198:201], v[74:77]
	v_mfma_f32_16x16x32_bf16 v[62:65], v[50:53], v[206:209], v[62:65]
	v_mfma_f32_16x16x32_bf16 v[58:61], v[66:69], v[206:209], v[58:61]
	v_mfma_f32_16x16x32_bf16 v[38:41], v[50:53], v[214:217], v[38:41]
	v_mfma_f32_16x16x32_bf16 v[34:37], v[66:69], v[214:217], v[34:37]
	v_mfma_f32_16x16x32_bf16 v[14:17], v[50:53], v[226:229], v[14:17]
	v_mfma_f32_16x16x32_bf16 v[10:13], v[66:69], v[226:229], v[10:13]
	v_mfma_f32_16x16x32_bf16 v[78:81], v[54:57], v[202:205], v[78:81]
	v_mfma_f32_16x16x32_bf16 v[74:77], v[70:73], v[202:205], v[74:77]
	v_mfma_f32_16x16x32_bf16 v[62:65], v[54:57], v[210:213], v[62:65]
	v_mfma_f32_16x16x32_bf16 v[58:61], v[70:73], v[210:213], v[58:61]
	v_mfma_f32_16x16x32_bf16 v[38:41], v[54:57], v[218:221], v[38:41]
	v_mfma_f32_16x16x32_bf16 v[34:37], v[70:73], v[218:221], v[34:37]
	v_mfma_f32_16x16x32_bf16 v[14:17], v[54:57], v[230:233], v[14:17]
	v_mfma_f32_16x16x32_bf16 v[10:13], v[70:73], v[230:233], v[10:13]
	s_setprio 0
	s_setprio 1
	v_mfma_f32_16x16x32_bf16 v[26:29], v[146:149], v[198:201], v[26:29]
	v_mfma_f32_16x16x32_bf16 v[70:73], v[150:153], v[202:205], v[26:29]
	v_mfma_f32_16x16x32_bf16 v[26:29], v[154:157], v[198:201], v[30:33]
	v_mfma_f32_16x16x32_bf16 v[66:69], v[158:161], v[202:205], v[26:29]
	v_mfma_f32_16x16x32_bf16 v[26:29], v[146:149], v[206:209], v[42:45]
	v_mfma_f32_16x16x32_bf16 v[54:57], v[150:153], v[210:213], v[26:29]
	v_mfma_f32_16x16x32_bf16 v[26:29], v[154:157], v[206:209], v[46:49]
	v_mfma_f32_16x16x32_bf16 v[22:25], v[146:149], v[214:217], v[22:25]
	v_mfma_f32_16x16x32_bf16 v[18:21], v[154:157], v[214:217], v[18:21]
	v_mfma_f32_16x16x32_bf16 v[6:9], v[146:149], v[226:229], v[6:9]
	v_mfma_f32_16x16x32_bf16 v[2:5], v[154:157], v[226:229], v[2:5]
	v_mfma_f32_16x16x32_bf16 v[50:53], v[158:161], v[210:213], v[26:29]
	v_mfma_f32_16x16x32_bf16 v[22:25], v[150:153], v[218:221], v[22:25]
	v_mfma_f32_16x16x32_bf16 v[18:21], v[158:161], v[218:221], v[18:21]
	v_mfma_f32_16x16x32_bf16 v[6:9], v[150:153], v[230:233], v[6:9]
	v_mfma_f32_16x16x32_bf16 v[2:5], v[158:161], v[230:233], v[2:5]
	s_setprio 0
	s_barrier
	s_add_i32 s27, s27, 2
	s_add_u32 s0, s0, 0x100
	s_addc_u32 s1, s1, 0
	s_add_u32 s16, s16, 0x100
	s_addc_u32 s22, s22, 0
	s_cmp_gt_u32 s27, 13
	s_cbranch_scc0 .LBB0_124
	v_readlane_b32 s0, v254, 21
	v_readlane_b32 s1, v254, 22
	s_and_b64 vcc, exec, s[0:1]
	s_cbranch_vccz .LBB0_127
	s_barrier

; #define LAS __attribute__((address_space(3)))
; __device__ __forceinline__ float fast_exp2(float x) { return __builtin_amdgcn_exp2f(x); }
; template <bool WIN>
; __device__ __forceinline__ void attn_item(bf16_t* U, const float* sink, int ci, int h, LAS unsigned char* wl, const LAS float* tbl, int lane_in) {
;     ...
;     unsigned koff[4], voff[4];
; #pragma unroll
;     for (int i = 0; i < 4; ++i) { const int key = 8 * i + (lane >> 3), ch = (lane & 7) ^ ((key >> 1) & 7); koff[i] = (unsigned)(key * LDU + kcol + ch * 8); }
; #pragma unroll
;     for (int i = 0; i < 4; ++i) { const int dh = i >> 1, kg = i & 1; voff[i] = (unsigned)((16 * kg + (lane >> 2)) * LDU + vcol + 32 * dh + 8 * (lane & 3)); }
;     ...
;     const int smin = 2 * tmin;
;     asm volatile("s_waitcnt lgkmcnt(0)" ::: "memory");
;     ATT_DMA(smin); ATT_DMA(smin + 1);
;     bf16x8 qr[2][4];
; #pragma unroll
;     for (int qh = 0; qh < 2; ++qh)
; #pragma unroll
;         for (int d0 = 0; d0 < 4; ++d0) qr[qh][d0] = *(const bf16x8*)(U + (size_t)(row0 + 32 * qh + r32) * LDU + qcol + 16 * d0 + 8 * hi);
;     u32x2 zr[2][2][4];
; #pragma unroll
;     for (int qh = 0; qh < 2; ++qh)
; #pragma unroll
;         for (int dh = 0; dh < 2; ++dh)
; #pragma unroll
;             for (int g = 0; g < 4; ++g) zr[qh][dh][g] = *(const u32x2*)(U + (size_t)(row0 + 32 * qh + r32) * LDU + 4 * hi + zcol + 32 * dh + 8 * g);
;     f32x16 o[2][2];
; #pragma unroll
;     for (int a = 0; a < 2; ++a)
; #pragma unroll
;         for (int b = 0; b < 2; ++b)
; #pragma unroll
;             for (int r = 0; r < 16; ++r) o[a][b][r] = 0.f;
;     float lrun[2];
;     const float slope2 = WIN ? (LOG2E * __builtin_amdgcn_exp2f(-(float)(h + 1))) : 0.f;
;     if (WIN) { lrun[0] = hi == 0 ? fast_exp2(sink[h] * LOG2E) : 0.f; lrun[1] = lrun[0]; }
;     else { lrun[0] = 0.f; lrun[1] = 0.f; }
;     const LAS float* th = tbl + h * 257;
;     int kfo[4];
; #pragma unroll
;     for (int d0 = 0; d0 < 4; ++d0) kfo[d0] = r32 * 128 + (((2 * d0 + hi) ^ ((r32 >> 1) & 7)) * 16);
;     const int vfo = 4096 + ((lane >> 4) & 1) * 32 + (lane & 3) * 8 + (4 * hi + ((lane & 15) >> 2)) * 64;
.LBB0_614:
	s_add_i32 s7, s7, 32
	s_mul_hi_i32 s11, s7, 0x2a00
	s_mulk_i32 s7, 0x2a00
	s_add_u32 s10, s82, s7
	s_addc_u32 s11, s83, s11
	s_mov_b32 m0, s31
	v_lshl_add_u64 v[6:7], v[146:147], 1, s[10:11]
	global_load_lds_dwordx4 v[6:7], off
	v_lshl_add_u64 v[6:7], v[166:167], 1, s[10:11]
	s_mov_b32 m0, s34
	v_lshl_add_u64 v[8:9], v[176:177], 1, s[10:11]
	global_load_lds_dwordx4 v[6:7], off
	v_lshl_add_u64 v[6:7], v[168:169], 1, s[10:11]
	s_mov_b32 m0, s35
	v_ashrrev_i32_e32 v4, 5, v2
	global_load_lds_dwordx4 v[6:7], off
	v_lshl_add_u64 v[6:7], v[170:171], 1, s[10:11]
	s_mov_b32 m0, s46
	v_ashrrev_i32_e32 v5, 31, v4
	global_load_lds_dwordx4 v[6:7], off
	v_lshl_add_u64 v[6:7], v[174:175], 1, s[10:11]
	s_mov_b32 m0, s47
	v_and_b32_e32 v10, 31, v2
	global_load_lds_dwordx4 v[6:7], off
	s_mov_b32 m0, s90
	v_lshl_add_u64 v[6:7], v[6:7], 0, 64
	global_load_lds_dwordx4 v[8:9], off
	s_mov_b32 m0, s91
	v_add_u32_e32 v11, s36, v10
	global_load_lds_dwordx4 v[6:7], off
	v_lshl_add_u64 v[6:7], v[8:9], 0, 64
	s_mov_b32 m0, s92
	v_lshlrev_b64 v[8:9], 3, v[4:5]
	global_load_lds_dwordx4 v[6:7], off
	v_lshlrev_b32_e32 v6, 3, v4
	v_ashrrev_i32_e32 v7, 31, v6
	v_sub_co_u32_e32 v8, vcc, 0, v8
	v_lshl_add_u64 v[6:7], v[6:7], 1, s[0:1]
	v_add_u32_e32 v12, 32, v11
	v_subb_co_u32_e32 v9, vcc, 0, v9, vcc
	v_mad_i64_i32 v[172:173], s[10:11], v11, s19, v[6:7]
	v_mad_i64_i32 v[148:149], s[10:11], v12, s19, v[6:7]
	v_lshl_add_u64 v[6:7], v[6:7], 0, v[8:9]
	v_mad_i64_i32 v[8:9], s[10:11], v11, s19, v[6:7]
	v_add_co_u32_e32 v8, vcc, s20, v8
	v_mad_i64_i32 v[6:7], s[10:11], v12, s19, v[6:7]
	s_nop 0
	v_addc_co_u32_e32 v9, vcc, 0, v9, vcc
	v_add_co_u32_e32 v6, vcc, s20, v6
	global_load_dwordx4 v[98:101], v[172:173], off offset:2560
	global_load_dwordx4 v[102:105], v[172:173], off offset:2592
	global_load_dwordx4 v[106:109], v[172:173], off offset:2624
	global_load_dwordx4 v[110:113], v[172:173], off offset:2656
	v_addc_co_u32_e32 v7, vcc, 0, v7, vcc
	global_load_dwordx4 v[114:117], v[148:149], off offset:2560
	global_load_dwordx4 v[118:121], v[148:149], off offset:2592
	global_load_dwordx4 v[122:125], v[148:149], off offset:2624
	global_load_dwordx4 v[126:129], v[148:149], off offset:2656
	global_load_dwordx2 v[198:199], v[8:9], off offset:1536
	global_load_dwordx2 v[192:193], v[8:9], off offset:1552
	global_load_dwordx2 v[190:191], v[8:9], off offset:1568
	global_load_dwordx2 v[188:189], v[8:9], off offset:1584
	global_load_dwordx2 v[186:187], v[8:9], off offset:1600
	global_load_dwordx2 v[182:183], v[8:9], off offset:1616
	global_load_dwordx2 v[180:181], v[8:9], off offset:1632
	global_load_dwordx2 v[178:179], v[8:9], off offset:1648
	global_load_dwordx2 v[164:165], v[6:7], off offset:1536
	global_load_dwordx2 v[162:163], v[6:7], off offset:1552
	global_load_dwordx2 v[160:161], v[6:7], off offset:1568
	global_load_dwordx2 v[158:159], v[6:7], off offset:1584
	global_load_dwordx2 v[156:157], v[6:7], off offset:1600
	global_load_dwordx2 v[154:155], v[6:7], off offset:1616
	global_load_dwordx2 v[152:153], v[6:7], off offset:1632
	global_load_dwordx2 v[150:151], v[6:7], off offset:1648
	v_lshrrev_b32_e32 v5, 1, v2
	v_bitop3_b32 v6, v5, v4, 7 bitop3:0x6c
	v_lshlrev_b32_e32 v201, 4, v6
	v_add_u32_e32 v6, 2, v4
	v_bitop3_b32 v6, v6, v5, 7 bitop3:0x78
	v_lshlrev_b32_e32 v13, 2, v4
	v_lshlrev_b32_e32 v202, 4, v6
	v_add_u32_e32 v6, 4, v4
	v_add_u32_e32 v4, 6, v4
	v_lshlrev_b32_e32 v2, 1, v2
	v_bitop3_b32 v6, v6, v5, 7 bitop3:0x78
	v_bitop3_b32 v4, v4, v5, 7 bitop3:0x78
	v_and_b32_e32 v205, 32, v2
	v_and_or_b32 v2, v3, 3, v13
	s_add_i32 s11, s6, 64
	s_lshl_b32 s6, s21, 5
	v_mov_b32_e32 v50, 0
	v_lshlrev_b32_e32 v200, 7, v10
	v_lshlrev_b32_e32 v203, 4, v6
	v_lshlrev_b32_e32 v204, 4, v4
	v_lshlrev_b32_e32 v206, 6, v2
	s_add_i32 s10, s36, 0xfffffe00
	v_sub_u32_e32 v207, v10, v13
	s_sub_i32 s36, 0, s6
	s_lshl_b32 s37, s21, 13
	v_mov_b32_e32 v51, v50
	v_mov_b32_e32 v52, v50
	v_mov_b32_e32 v53, v50
	v_mov_b32_e32 v54, v50
	v_mov_b32_e32 v55, v50
	v_mov_b32_e32 v56, v50
	v_mov_b32_e32 v57, v50
	v_mov_b32_e32 v58, v50
	v_mov_b32_e32 v59, v50
	v_mov_b32_e32 v60, v50
	v_mov_b32_e32 v61, v50
	v_mov_b32_e32 v62, v50
	v_mov_b32_e32 v63, v50
	v_mov_b32_e32 v64, v50
	v_mov_b32_e32 v65, v50
	v_mov_b32_e32 v34, v50
	v_mov_b32_e32 v35, v50
	v_mov_b32_e32 v36, v50
	v_mov_b32_e32 v37, v50
	v_mov_b32_e32 v38, v50
	v_mov_b32_e32 v39, v50
	v_mov_b32_e32 v40, v50
	v_mov_b32_e32 v41, v50
	v_mov_b32_e32 v42, v50
	v_mov_b32_e32 v43, v50
	v_mov_b32_e32 v44, v50
	v_mov_b32_e32 v45, v50
	v_mov_b32_e32 v46, v50
	v_mov_b32_e32 v47, v50
	v_mov_b32_e32 v48, v50
	v_mov_b32_e32 v49, v50
	v_mov_b32_e32 v18, v50
	v_mov_b32_e32 v19, v50
	v_mov_b32_e32 v20, v50
	v_mov_b32_e32 v21, v50
	v_mov_b32_e32 v22, v50
	v_mov_b32_e32 v23, v50
	v_mov_b32_e32 v24, v50
	v_mov_b32_e32 v25, v50
	v_mov_b32_e32 v26, v50
	v_mov_b32_e32 v27, v50
	v_mov_b32_e32 v28, v50
	v_mov_b32_e32 v29, v50
	v_mov_b32_e32 v30, v50
	v_mov_b32_e32 v31, v50
	v_mov_b32_e32 v32, v50
	v_mov_b32_e32 v33, v50
	v_mov_b32_e32 v2, v50
	v_mov_b32_e32 v3, v50
	v_mov_b32_e32 v4, v50
	v_mov_b32_e32 v5, v50
	v_mov_b32_e32 v6, v50
	v_mov_b32_e32 v7, v50
	v_mov_b32_e32 v8, v50
	v_mov_b32_e32 v9, v50
	v_mov_b32_e32 v10, v50
	v_mov_b32_e32 v11, v50
	v_mov_b32_e32 v12, v50
	v_mov_b32_e32 v13, v50
	v_mov_b32_e32 v14, v50
	v_mov_b32_e32 v15, v50
	v_mov_b32_e32 v16, v50
	v_mov_b32_e32 v17, v50
	v_mov_b32_e32 v184, v50
	v_mov_b32_e32 v185, v50
	v_lshlrev_b32_e32 v212, 1, v146
	v_lshlrev_b32_e32 v213, 1, v166
	v_lshlrev_b32_e32 v214, 1, v168
	v_lshlrev_b32_e32 v215, 1, v170
	v_lshlrev_b32_e32 v216, 1, v174
	v_lshlrev_b32_e32 v217, 1, v176
	v_lshl_add_u32 v218, v174, 1, 64
	v_lshl_add_u32 v219, v176, 1, 64
	s_waitcnt vmcnt(0)
	s_branch .LBB0_616

; template <bool WIN>
; __device__ __forceinline__ void attn_item(bf16_t* U, const float* sink, int ci, int h, LAS unsigned char* wl, const LAS float* tbl, int lane_in) {
;     ...
;             bf16x8 kf[4];
; #pragma unroll
;             for (int d0 = 0; d0 < 4; ++d0) kf[d0] = *(const LAS bf16x8*)(wb + kfo[d0]);
;             asm volatile("s_waitcnt lgkmcnt(0)" ::: "memory");
;             __builtin_amdgcn_sched_barrier(0);
; #pragma unroll
;             for (int d0 = 0; d0 < 4; ++d0) {
;                 Cq[0] = __builtin_amdgcn_mfma_f32_32x32x16_bf16(kf[d0], qr[0][d0], Cq[0], 0, 0, 0);
;                 Cq[1] = __builtin_amdgcn_mfma_f32_32x32x16_bf16(kf[d0], qr[1][d0], Cq[1], 0, 0, 0);
;             }
;         }
;         __builtin_amdgcn_sched_barrier(0);
;         bf16x8 vf[2][2];
;         { s16x4 tl[4], tu[4];
;             const unsigned va = (unsigned)(uintptr_t)(wb + vfo);
;             asm volatile("ds_read_b64_tr_b16 %0, %8\n\tds_read_b64_tr_b16 %1, %8 offset:512\n\tds_read_b64_tr_b16 %2, %8 offset:1024\n\tds_read_b64_tr_b16 %3, %8 offset:1536\n\t"
;                          "ds_read_b64_tr_b16 %4, %8 offset:2048\n\tds_read_b64_tr_b16 %5, %8 offset:2560\n\tds_read_b64_tr_b16 %6, %8 offset:3072\n\tds_read_b64_tr_b16 %7, %8 offset:3584\n\t"
;                          "s_waitcnt lgkmcnt(0)"
;                          : "=&v"(tl[0]), "=&v"(tu[0]), "=&v"(tl[1]), "=&v"(tu[1]), "=&v"(tl[2]), "=&v"(tu[2]), "=&v"(tl[3]), "=&v"(tu[3]) : "v"(va) : "memory");
; #pragma unroll
;             for (int i = 0; i < 4; ++i) vf[i >> 1][i & 1] = (bf16x8){tl[i][0], tl[i][1], tl[i][2], tl[i][3], tu[i][0], tu[i][1], tu[i][2], tu[i][3]}; }
;         if (s + 2 < NS) ATT_DMA(s + 2);
; #pragma unroll
;         for (int qh = 0; qh < 2; ++qh) {
;             f32x16 C0 = Cq[qh];
;             typedef float f32x2v __attribute__((ext_vector_type(2)));
;             f32x2v ps2 = (f32x2v){0.f, 0.f};
; #pragma unroll
;             for (int r = 0; r < 16; r += 2) { C0[r] = fast_exp2(C0[r]); C0[r + 1] = fast_exp2(C0[r + 1]); ps2 += (f32x2v){C0[r], C0[r + 1]}; }
;             lrun[qh] += ps2.x + ps2.y;
;             u32x4 w0, w1;
; #pragma unroll
;             for (int q = 0; q < 4; ++q) { w0[q] = cvt_pk_bf16(C0[2 * q], C0[2 * q + 1]); w1[q] = cvt_pk_bf16(C0[8 + 2 * q], C0[8 + 2 * q + 1]); }
;             const bf16x8 pw0 = __builtin_bit_cast(bf16x8, w0), pw1 = __builtin_bit_cast(bf16x8, w1);
.LBB0_624:
	s_and_b32 s6, s37, 0x2000
	s_add_i32 s6, s22, s6
	v_add3_u32 v130, s6, v201, v200
	v_add3_u32 v134, s6, v202, v200
	v_add3_u32 v138, s6, v203, v200
	v_add3_u32 v142, s6, v204, v200
	ds_read_b128 v[130:133], v130
	ds_read_b128 v[134:137], v134
	ds_read_b128 v[138:141], v138
	ds_read_b128 v[142:145], v142
	s_waitcnt lgkmcnt(0)
	s_waitcnt lgkmcnt(0)
	v_mfma_f32_32x32x16_bf16 v[82:97], v[130:133], v[98:101], v[82:97]
	v_mfma_f32_32x32x16_bf16 v[66:81], v[130:133], v[114:117], v[66:81]
	v_mfma_f32_32x32x16_bf16 v[82:97], v[134:137], v[102:105], v[82:97]
	v_mfma_f32_32x32x16_bf16 v[66:81], v[134:137], v[118:121], v[66:81]
	v_mfma_f32_32x32x16_bf16 v[82:97], v[138:141], v[106:109], v[82:97]
	v_mfma_f32_32x32x16_bf16 v[66:81], v[138:141], v[122:125], v[66:81]
	v_mfma_f32_32x32x16_bf16 v[82:97], v[142:145], v[110:113], v[82:97]
	v_mfma_f32_32x32x16_bf16 v[66:81], v[142:145], v[126:129], v[66:81]
	v_add3_u32 v130, s6, v205, v1
	v_add3_u32 v208, v130, v206, s20
	ds_read_b64_tr_b16 v[142:143], v208
	ds_read_b64_tr_b16 v[144:145], v208 offset:512
	ds_read_b64_tr_b16 v[138:139], v208 offset:1024
	ds_read_b64_tr_b16 v[140:141], v208 offset:1536
	ds_read_b64_tr_b16 v[134:135], v208 offset:2048
	ds_read_b64_tr_b16 v[136:137], v208 offset:2560
	ds_read_b64_tr_b16 v[130:131], v208 offset:3072
	ds_read_b64_tr_b16 v[132:133], v208 offset:3584
	s_waitcnt lgkmcnt(0)
	s_cmp_gt_u32 s21, 15
	s_cbranch_scc1 .LBB0_615
	s_cmp_lt_u32 s21, 14
	s_cselect_b64 s[6:7], -1, 0
	s_and_b64 s[6:7], s[4:5], s[6:7]
	s_and_b32 s38, s11, 0x3c0
	s_and_b64 s[6:7], s[6:7], exec
	s_cselect_b32 s6, s33, s10
	s_and_b32 s39, s21, 1
	s_lshl_b32 s7, s39, 5
	s_or_b32 s7, s38, s7
	s_add_i32 s6, s7, s6
	s_mul_hi_i32 s7, s6, 0x2a00
	s_mulk_i32 s6, 0x2a00
	s_add_u32 s6, s82, s6
	s_addc_u32 s7, s83, s7
	s_lshl_b32 s38, s39, 13
	s_add_i32 s38, s22, s38
	s_mov_b64 s[40:41], s[6:7]
	s_mov_b32 s42, s38
	s_branch .L615d
.L615d:
	s_mov_b32 m0, s42
	s_nop 0
	global_load_lds_dwordx4 v212, s[40:41]
	s_add_i32 m0, s42, 0x400
	s_nop 0
	global_load_lds_dwordx4 v213, s[40:41]
	s_nop 0
	v_exp_f32_e32 v82, v82
	v_exp_f32_e32 v83, v83
	v_exp_f32_e32 v84, v84
	v_exp_f32_e32 v85, v85
	v_exp_f32_e32 v210, v86
	v_exp_f32_e32 v211, v87
	v_pk_add_f32 v[208:209], v[82:83], 0 op_sel_hi:[1,0]
	v_exp_f32_e32 v66, v66
	s_add_i32 m0, s42, 0x800
	v_pk_add_f32 v[208:209], v[84:85], v[208:209]
	global_load_lds_dwordx4 v214, s[40:41]
	v_exp_f32_e32 v67, v67
	v_pk_add_f32 v[86:87], v[210:211], v[208:209]
	v_exp_f32_e32 v208, v88
	v_exp_f32_e32 v209, v89
	v_cvt_pk_bf16_f32 v82, v82, v83
	v_cvt_pk_bf16_f32 v83, v84, v85
	v_cvt_pk_bf16_f32 v84, v210, v211
	v_cvt_pk_bf16_f32 v85, v208, v209
	v_exp_f32_e32 v68, v68
	s_add_i32 m0, s42, 0xc00
	v_exp_f32_e32 v69, v69
	global_load_lds_dwordx4 v215, s[40:41]
	v_mfma_f32_32x32x16_bf16 v[50:65], v[142:145], v[82:85], v[50:65]
	v_exp_f32_e32 v88, v90
	v_exp_f32_e32 v89, v91
	v_exp_f32_e32 v90, v92
	v_exp_f32_e32 v91, v93
	v_exp_f32_e32 v92, v94
	v_exp_f32_e32 v93, v95
	v_pk_add_f32 v[86:87], v[208:209], v[86:87]
	v_mfma_f32_32x32x16_bf16 v[34:49], v[134:137], v[82:85], v[34:49]
	v_exp_f32_e32 v84, v70
	v_exp_f32_e32 v85, v71
	s_add_i32 m0, s42, 0x1000
	v_pk_add_f32 v[82:83], v[66:67], 0 op_sel_hi:[1,0]
	global_load_lds_dwordx4 v216, s[40:41]
	v_cvt_pk_bf16_f32 v66, v66, v67
	v_pk_add_f32 v[82:83], v[68:69], v[82:83]
	v_cvt_pk_bf16_f32 v67, v68, v69
	v_pk_add_f32 v[70:71], v[84:85], v[82:83]
	v_exp_f32_e32 v82, v72
	v_exp_f32_e32 v83, v73
	v_exp_f32_e32 v72, v74
	v_exp_f32_e32 v73, v75
	v_exp_f32_e32 v74, v76
	v_exp_f32_e32 v75, v77
	v_exp_f32_e32 v76, v78
	s_add_i32 m0, s42, 0x1400
	v_exp_f32_e32 v77, v79
	global_load_lds_dwordx4 v217, s[40:41]
	v_cvt_pk_bf16_f32 v68, v84, v85
	v_cvt_pk_bf16_f32 v69, v82, v83
	v_exp_f32_e32 v94, v96
	v_exp_f32_e32 v95, v97
	v_pk_add_f32 v[70:71], v[82:83], v[70:71]
	v_exp_f32_e32 v78, v80
	v_exp_f32_e32 v79, v81
	v_mfma_f32_32x32x16_bf16 v[18:33], v[142:145], v[66:69], v[18:33]
	v_add_f32_e64 v86, v88, v86
	v_add_f32_e64 v87, v89, v87
	v_add_f32_e64 v70, v72, v70
	s_add_i32 m0, s42, 0x1800
	v_add_f32_e64 v71, v73, v71
	global_load_lds_dwordx4 v218, s[40:41]
	v_add_f32_e64 v86, v90, v86
	v_add_f32_e64 v87, v91, v87
	v_pk_add_f32 v[70:71], v[74:75], v[70:71]
	v_pk_add_f32 v[86:87], v[92:93], v[86:87]
	v_pk_add_f32 v[70:71], v[76:77], v[70:71]
	v_pk_add_f32 v[96:97], v[94:95], v[86:87]
	v_mfma_f32_32x32x16_bf16 v[2:17], v[134:137], v[66:69], v[2:17]
	v_add_f32_e64 v70, v78, v70
	v_add_f32_e64 v71, v79, v71
	v_mov_b32_e32 v80, v96
	v_mov_b32_e32 v81, v70
	s_add_i32 m0, s42, 0x1c00
	v_mov_b32_e32 v70, v97
	global_load_lds_dwordx4 v219, s[40:41]
	v_pk_add_f32 v[70:71], v[80:81], v[70:71]
	v_cvt_pk_bf16_f32 v86, v88, v89
	v_cvt_pk_bf16_f32 v87, v90, v91
	v_cvt_pk_bf16_f32 v88, v92, v93
	v_cvt_pk_bf16_f32 v89, v94, v95
	v_pk_add_f32 v[184:185], v[184:185], v[70:71]
	v_cvt_pk_bf16_f32 v70, v72, v73
	v_cvt_pk_bf16_f32 v71, v74, v75
	v_cvt_pk_bf16_f32 v72, v76, v77
	v_cvt_pk_bf16_f32 v73, v78, v79
	v_mfma_f32_32x32x16_bf16 v[50:65], v[138:141], v[86:89], v[50:65]
	s_add_i32 s6, s21, 1
	s_add_i32 s11, s11, 32
	s_sub_i32 s36, s36, 32
	s_addk_i32 s37, 0x2000
	s_cmp_lt_u32 s21, 17
	s_mov_b32 s21, s6
	v_mfma_f32_32x32x16_bf16 v[34:49], v[130:133], v[86:89], v[34:49]
	v_mfma_f32_32x32x16_bf16 v[18:33], v[138:141], v[70:73], v[18:33]
	v_mfma_f32_32x32x16_bf16 v[2:17], v[130:133], v[70:73], v[2:17]
	s_cbranch_scc0 .LBB0_599
	s_branch .LBB0_616

; #define LAS __attribute__((address_space(3)))
; __device__ __forceinline__ float fast_exp2(float x) { return __builtin_amdgcn_exp2f(x); }
; template <bool WIN>
; __device__ __forceinline__ void attn_item(bf16_t* U, const float* sink, int ci, int h, LAS unsigned char* wl, const LAS float* tbl, int lane_in) {
;     ...
;     f32x16 o[2][2];
; #pragma unroll
;     for (int a = 0; a < 2; ++a)
; #pragma unroll
;         for (int b = 0; b < 2; ++b)
; #pragma unroll
;             for (int r = 0; r < 16; ++r) o[a][b][r] = 0.f;
;     float lrun[2];
;     const float slope2 = WIN ? (LOG2E * __builtin_amdgcn_exp2f(-(float)(h + 1))) : 0.f;
;     if (WIN) { lrun[0] = hi == 0 ? fast_exp2(sink[h] * LOG2E) : 0.f; lrun[1] = lrun[0]; }
;     else { lrun[0] = 0.f; lrun[1] = 0.f; }
;     const LAS float* th = tbl + h * 257;
;     int kfo[4];
; #pragma unroll
;     for (int d0 = 0; d0 < 4; ++d0) kfo[d0] = r32 * 128 + (((2 * d0 + hi) ^ ((r32 >> 1) & 7)) * 16);
;     const int vfo = 4096 + ((lane >> 4) & 1) * 32 + (lane & 3) * 8 + (4 * hi + ((lane & 15) >> 2)) * 64;
; #pragma unroll 1
;     for (int s = smin; s < NS; ++s) {
;         if (s + 1 < NS) asm volatile("s_waitcnt vmcnt(8)" ::: "memory"); else asm volatile("s_waitcnt vmcnt(0)" ::: "memory");
;         const LAS unsigned char* wb = wl + (s & 1) * 8192;
;         f32x16 Cq[2];
; #pragma unroll
;         for (int qh = 0; qh < 2; ++qh) {
;             f32x16 C0;
;             const int iq = 32 * qh + r32;
;             const float nm = -slope2 * (float)(128 + iq);
;             if (WIN) {
;                 if (s < 4) { const float b0 = slope2 * (float)(32 * s + 4 * hi) + nm;
; #pragma unroll
;                     for (int r = 0; r < 16; ++r) C0[r] = __builtin_fmaf(slope2, (float)((r & 3) + 8 * (r >> 2)), b0);
;                 } else { const int base = 128 + iq - 32 * s - 4 * hi; const float b1 = slope2 * (float)(128 + iq) + nm;
; #pragma unroll
;                     for (int r = 0; r < 16; ++r) { const int cr = (r & 3) + 8 * (r >> 2); C0[r] = __builtin_fmaf(-slope2, fabsf((float)(base - cr)), b1); } }
.LBB0_645:
	s_or_b64 exec, exec, s[18:19]
	v_lshrrev_b32_e32 v3, 1, v1
	v_bitop3_b32 v6, v3, v2, 7 bitop3:0x6c
	v_lshlrev_b32_e32 v231, 4, v6
	v_add_u32_e32 v6, 2, v2
	v_bitop3_b32 v6, v6, v3, 7 bitop3:0x78
	v_lshlrev_b32_e32 v229, 2, v2
	v_lshlrev_b32_e32 v232, 4, v6
	v_add_u32_e32 v6, 4, v2
	v_add_u32_e32 v2, 6, v2
	v_lshlrev_b32_e32 v1, 1, v1
	v_bitop3_b32 v2, v2, v3, 7 bitop3:0x78
	v_and_b32_e32 v235, 32, v1
	v_and_or_b32 v1, v4, 3, v229
	v_or_b32_e32 v204, 0x80, v5
	v_or_b32_e32 v210, 0xa0, v5
	v_lshlrev_b32_e32 v234, 4, v2
	v_lshlrev_b32_e32 v236, 6, v1
	v_cvt_f32_ubyte0_e32 v1, v204
	v_cvt_f32_ubyte0_e32 v2, v210
	v_mul_f32_e64 v237, -v146, v1
	v_mul_f32_e64 v238, -v146, v2
	v_bitop3_b32 v6, v6, v3, 7 bitop3:0x78
	s_lshl_b32 s75, s73, 9
	v_fma_f32 v206, v146, v1, v237
	v_fma_f32 v212, v146, v2, v238
	v_add_u32_e32 v214, 0x78, v5
	v_add_u32_e32 v216, 0x70, v5
	v_add_u32_e32 v218, 0x68, v5
	v_add_u32_e32 v220, 0x98, v5
	v_add_u32_e32 v222, 0x90, v5
	v_add_u32_e32 v224, 0x88, v5
	v_lshlrev_b32_e32 v230, 7, v5
	v_lshlrev_b32_e32 v233, 4, v6
	s_add_i32 s74, s72, 0xffffff80
	s_add_i32 s75, s75, 0x83c0
	v_or_b32_e32 v1, 3, v229
	v_or_b32_e32 v208, 2, v229
	v_mov_b32_e32 v205, v210
	v_mov_b32_e32 v213, v212
	v_mov_b32_e32 v209, v220
	v_mov_b32_e32 v211, v222
	v_mov_b32_e32 v215, v224
	v_mov_b32_e32 v217, v204
	v_mov_b32_e32 v207, v206
	v_mov_b32_e32 v219, v214
	v_mov_b32_e32 v221, v216
	v_mov_b32_e32 v223, v218
	s_lshl_b32 s84, s55, 5
	s_lshl_b32 s85, s55, 13
	v_mov_b32_e32 v35, v34
	v_mov_b32_e32 v36, v34
	v_mov_b32_e32 v37, v34
	v_mov_b32_e32 v38, v34
	v_mov_b32_e32 v39, v34
	v_mov_b32_e32 v40, v34
	v_mov_b32_e32 v41, v34
	v_mov_b32_e32 v42, v34
	v_mov_b32_e32 v43, v34
	v_mov_b32_e32 v44, v34
	v_mov_b32_e32 v45, v34
	v_mov_b32_e32 v46, v34
	v_mov_b32_e32 v47, v34
	v_mov_b32_e32 v48, v34
	v_mov_b32_e32 v49, v34
	v_mov_b32_e32 v50, v34
	v_mov_b32_e32 v51, v34
	v_mov_b32_e32 v52, v34
	v_mov_b32_e32 v53, v34
	v_mov_b32_e32 v54, v34
	v_mov_b32_e32 v55, v34
	v_mov_b32_e32 v56, v34
	v_mov_b32_e32 v57, v34
	v_mov_b32_e32 v58, v34
	v_mov_b32_e32 v59, v34
	v_mov_b32_e32 v60, v34
	v_mov_b32_e32 v61, v34
	v_mov_b32_e32 v62, v34
	v_mov_b32_e32 v63, v34
	v_mov_b32_e32 v64, v34
	v_mov_b32_e32 v65, v34
	v_mov_b32_e32 v18, v34
	v_mov_b32_e32 v19, v34
	v_mov_b32_e32 v20, v34
	v_mov_b32_e32 v21, v34
	v_mov_b32_e32 v22, v34
	v_mov_b32_e32 v23, v34
	v_mov_b32_e32 v24, v34
	v_mov_b32_e32 v25, v34
	v_mov_b32_e32 v26, v34
	v_mov_b32_e32 v27, v34
	v_mov_b32_e32 v28, v34
	v_mov_b32_e32 v29, v34
	v_mov_b32_e32 v30, v34
	v_mov_b32_e32 v31, v34
	v_mov_b32_e32 v32, v34
	v_mov_b32_e32 v33, v34
	v_mov_b32_e32 v2, v34
	v_mov_b32_e32 v3, v34
	v_mov_b32_e32 v4, v34
	v_mov_b32_e32 v5, v34
	v_mov_b32_e32 v6, v34
	v_mov_b32_e32 v7, v34
	v_mov_b32_e32 v8, v34
	v_mov_b32_e32 v9, v34
	v_mov_b32_e32 v10, v34
	v_mov_b32_e32 v11, v34
	v_mov_b32_e32 v12, v34
	v_mov_b32_e32 v13, v34
	v_mov_b32_e32 v14, v34
	v_mov_b32_e32 v15, v34
	v_mov_b32_e32 v16, v34
	v_mov_b32_e32 v17, v34
	v_mov_b32_e32 v171, v170
	v_lshlrev_b32_e32 v244, 1, v150
	v_lshlrev_b32_e32 v245, 1, v186
	v_lshlrev_b32_e32 v246, 1, v188
	v_lshlrev_b32_e32 v247, 1, v190
	v_lshlrev_b32_e32 v248, 1, v198
	v_lshlrev_b32_e32 v249, 1, v200
	v_lshl_add_u32 v250, v198, 1, 64
	v_lshl_add_u32 v251, v200, 1, 64
	s_waitcnt vmcnt(0)
	s_branch .LBB0_647

; template <bool WIN>
; __device__ __forceinline__ void attn_item(bf16_t* U, const float* sink, int ci, int h, LAS unsigned char* wl, const LAS float* tbl, int lane_in) {
;     ...
;             bf16x8 kf[4];
; #pragma unroll
;             for (int d0 = 0; d0 < 4; ++d0) kf[d0] = *(const LAS bf16x8*)(wb + kfo[d0]);
;             asm volatile("s_waitcnt lgkmcnt(0)" ::: "memory");
;             __builtin_amdgcn_sched_barrier(0);
; #pragma unroll
;             for (int d0 = 0; d0 < 4; ++d0) {
;                 Cq[0] = __builtin_amdgcn_mfma_f32_32x32x16_bf16(kf[d0], qr[0][d0], Cq[0], 0, 0, 0);
;                 Cq[1] = __builtin_amdgcn_mfma_f32_32x32x16_bf16(kf[d0], qr[1][d0], Cq[1], 0, 0, 0);
;             }
;         }
;         __builtin_amdgcn_sched_barrier(0);
;         bf16x8 vf[2][2];
;         { s16x4 tl[4], tu[4];
;             const unsigned va = (unsigned)(uintptr_t)(wb + vfo);
;             asm volatile("ds_read_b64_tr_b16 %0, %8\n\tds_read_b64_tr_b16 %1, %8 offset:512\n\tds_read_b64_tr_b16 %2, %8 offset:1024\n\tds_read_b64_tr_b16 %3, %8 offset:1536\n\t"
;                          "ds_read_b64_tr_b16 %4, %8 offset:2048\n\tds_read_b64_tr_b16 %5, %8 offset:2560\n\tds_read_b64_tr_b16 %6, %8 offset:3072\n\tds_read_b64_tr_b16 %7, %8 offset:3584\n\t"
;                          "s_waitcnt lgkmcnt(0)"
;                          : "=&v"(tl[0]), "=&v"(tu[0]), "=&v"(tl[1]), "=&v"(tu[1]), "=&v"(tl[2]), "=&v"(tu[2]), "=&v"(tl[3]), "=&v"(tu[3]) : "v"(va) : "memory");
; #pragma unroll
;             for (int i = 0; i < 4; ++i) vf[i >> 1][i & 1] = (bf16x8){tl[i][0], tl[i][1], tl[i][2], tl[i][3], tu[i][0], tu[i][1], tu[i][2], tu[i][3]}; }
;         if (s + 2 < NS) ATT_DMA(s + 2);
; #pragma unroll
;         for (int qh = 0; qh < 2; ++qh) {
;             f32x16 C0 = Cq[qh];
;             typedef float f32x2v __attribute__((ext_vector_type(2)));
;             f32x2v ps2 = (f32x2v){0.f, 0.f};
; #pragma unroll
;             for (int r = 0; r < 16; r += 2) { C0[r] = fast_exp2(C0[r]); C0[r + 1] = fast_exp2(C0[r + 1]); ps2 += (f32x2v){C0[r], C0[r + 1]}; }
;             lrun[qh] += ps2.x + ps2.y;
;             u32x4 w0, w1;
; #pragma unroll
;             for (int q = 0; q < 4; ++q) { w0[q] = cvt_pk_bf16(C0[2 * q], C0[2 * q + 1]); w1[q] = cvt_pk_bf16(C0[8 + 2 * q], C0[8 + 2 * q + 1]); }
;             const bf16x8 pw0 = __builtin_bit_cast(bf16x8, w0), pw1 = __builtin_bit_cast(bf16x8, w1);
.LBB0_659:
	s_and_b32 s20, s85, 0x2000
	s_add_i32 s20, s22, s20
	v_add3_u32 v130, s20, v231, v230
	v_add3_u32 v134, s20, v232, v230
	v_add3_u32 v138, s20, v233, v230
	v_add3_u32 v142, s20, v234, v230
	ds_read_b128 v[130:133], v130
	ds_read_b128 v[134:137], v134
	ds_read_b128 v[138:141], v138
	ds_read_b128 v[142:145], v142
	s_waitcnt lgkmcnt(0)
	s_waitcnt lgkmcnt(0)
	v_mfma_f32_32x32x16_bf16 v[66:81], v[130:133], v[98:101], v[66:81]
	v_mfma_f32_32x32x16_bf16 v[82:97], v[130:133], v[114:117], v[82:97]
	v_mfma_f32_32x32x16_bf16 v[66:81], v[134:137], v[102:105], v[66:81]
	v_mfma_f32_32x32x16_bf16 v[82:97], v[134:137], v[118:121], v[82:97]
	v_mfma_f32_32x32x16_bf16 v[66:81], v[138:141], v[106:109], v[66:81]
	v_mfma_f32_32x32x16_bf16 v[82:97], v[138:141], v[122:125], v[82:97]
	v_mfma_f32_32x32x16_bf16 v[66:81], v[142:145], v[110:113], v[66:81]
	v_mfma_f32_32x32x16_bf16 v[82:97], v[142:145], v[126:129], v[82:97]
	v_add3_u32 v130, s20, v235, v228
	s_movk_i32 s20, 0x1000
	v_add3_u32 v239, v130, v236, s20
	ds_read_b64_tr_b16 v[142:143], v239
	ds_read_b64_tr_b16 v[144:145], v239 offset:512
	ds_read_b64_tr_b16 v[138:139], v239 offset:1024
	ds_read_b64_tr_b16 v[140:141], v239 offset:1536
	ds_read_b64_tr_b16 v[134:135], v239 offset:2048
	ds_read_b64_tr_b16 v[136:137], v239 offset:2560
	ds_read_b64_tr_b16 v[130:131], v239 offset:3072
	ds_read_b64_tr_b16 v[132:133], v239 offset:3584
	s_waitcnt lgkmcnt(0)
	s_andn2_b64 vcc, exec, s[18:19]
	s_cbranch_vccnz .LBB0_646
	s_cmp_lt_u32 s55, 2
	s_cselect_b64 s[18:19], -1, 0
	s_add_i32 s20, s84, 64
	s_and_b32 s20, s20, 0xc0
	s_and_b64 s[18:19], s[44:45], s[18:19]
	s_add_i32 s20, s74, s20
	s_and_b64 s[18:19], s[18:19], exec
	s_cselect_b32 s18, s75, s20
	s_and_b32 s20, s55, 1
	s_lshl_b32 s19, s20, 5
	s_add_i32 s18, s18, s19
	s_mul_hi_i32 s19, s18, 0x2a00
	s_mulk_i32 s18, 0x2a00
	s_add_u32 s18, s82, s18
	s_addc_u32 s19, s83, s19
	s_lshl_b32 s20, s20, 13
	s_add_i32 s20, s22, s20
	s_mov_b64 s[88:89], s[18:19]
	s_mov_b32 s32, s20
	s_branch .L646d
.L646d:
	s_mov_b32 m0, s32
	s_nop 0
	global_load_lds_dwordx4 v244, s[88:89]
	s_add_i32 m0, s32, 0x400
	s_nop 0
	global_load_lds_dwordx4 v245, s[88:89]
	v_exp_f32_e32 v66, v66
	v_exp_f32_e32 v67, v67
	v_exp_f32_e32 v68, v68
	v_exp_f32_e32 v69, v69
	v_exp_f32_e32 v242, v70
	v_exp_f32_e32 v243, v71
	v_pk_add_f32 v[240:241], v[66:67], 0 op_sel_hi:[1,0]
	v_cvt_pk_bf16_f32 v66, v66, v67
	s_add_i32 m0, s32, 0x800
	v_pk_add_f32 v[240:241], v[68:69], v[240:241]
	global_load_lds_dwordx4 v246, s[88:89]
	v_cvt_pk_bf16_f32 v67, v68, v69
	v_pk_add_f32 v[70:71], v[242:243], v[240:241]
	v_exp_f32_e32 v240, v72
	v_exp_f32_e32 v241, v73
	v_cvt_pk_bf16_f32 v68, v242, v243
	v_exp_f32_e32 v72, v74
	v_exp_f32_e32 v73, v75
	v_cvt_pk_bf16_f32 v69, v240, v241
	v_exp_f32_e32 v74, v76
	s_add_i32 m0, s32, 0xc00
	v_exp_f32_e32 v75, v77
	global_load_lds_dwordx4 v247, s[88:89]
	v_mfma_f32_32x32x16_bf16 v[34:49], v[142:145], v[66:69], v[34:49]
	v_exp_f32_e32 v76, v78
	v_exp_f32_e32 v77, v79
	v_pk_add_f32 v[70:71], v[240:241], v[70:71]
	v_exp_f32_e32 v78, v80
	v_exp_f32_e32 v79, v81
	v_pk_add_f32 v[70:71], v[72:73], v[70:71]
	s_add_i32 s18, s55, 1
	v_mfma_f32_32x32x16_bf16 v[50:65], v[134:137], v[66:69], v[50:65]
	v_add_f32_e64 v70, v74, v70
	v_add_f32_e64 v71, v75, v71
	s_add_i32 m0, s32, 0x1000
	v_exp_f32_e32 v66, v82
	global_load_lds_dwordx4 v248, s[88:89]
	v_pk_add_f32 v[70:71], v[76:77], v[70:71]
	v_exp_f32_e32 v67, v83
	v_pk_add_f32 v[80:81], v[78:79], v[70:71]
	v_cvt_pk_bf16_f32 v70, v72, v73
	v_cvt_pk_bf16_f32 v71, v74, v75
	v_cvt_pk_bf16_f32 v72, v76, v77
	v_cvt_pk_bf16_f32 v73, v78, v79
	v_exp_f32_e32 v74, v86
	v_exp_f32_e32 v75, v87
	v_mfma_f32_32x32x16_bf16 v[34:49], v[138:141], v[70:73], v[34:49]
	v_exp_f32_e32 v76, v88
	s_add_i32 m0, s32, 0x1400
	v_exp_f32_e32 v77, v89
	global_load_lds_dwordx4 v249, s[88:89]
	v_pk_add_f32 v[68:69], v[66:67], 0 op_sel_hi:[1,0]
	v_exp_f32_e32 v78, v92
	v_exp_f32_e32 v79, v93
	v_exp_f32_e32 v82, v94
	v_exp_f32_e32 v83, v95
	v_mfma_f32_32x32x16_bf16 v[50:65], v[130:133], v[70:73], v[50:65]
	v_exp_f32_e32 v72, v84
	v_exp_f32_e32 v73, v85
	v_exp_f32_e32 v70, v90
	v_exp_f32_e32 v71, v91
	v_exp_f32_e32 v84, v96
	s_add_i32 m0, s32, 0x1800
	v_pk_add_f32 v[68:69], v[72:73], v[68:69]
	global_load_lds_dwordx4 v250, s[88:89]
	v_exp_f32_e32 v85, v97
	v_pk_add_f32 v[68:69], v[74:75], v[68:69]
	v_mov_b32_e32 v86, v80
	v_pk_add_f32 v[68:69], v[76:77], v[68:69]
	v_cvt_pk_bf16_f32 v66, v66, v67
	v_pk_add_f32 v[68:69], v[70:71], v[68:69]
	v_cvt_pk_bf16_f32 v67, v72, v73
	v_pk_add_f32 v[68:69], v[78:79], v[68:69]
	v_cvt_pk_bf16_f32 v70, v70, v71
	v_pk_add_f32 v[68:69], v[82:83], v[68:69]
	v_cvt_pk_bf16_f32 v71, v78, v79
	s_add_i32 m0, s32, 0x1c00
	v_pk_add_f32 v[68:69], v[84:85], v[68:69]
	global_load_lds_dwordx4 v251, s[88:89]
	v_cvt_pk_bf16_f32 v72, v82, v83
	v_mov_b32_e32 v87, v68
	v_mov_b32_e32 v68, v81
	v_pk_add_f32 v[68:69], v[86:87], v[68:69]
	v_cvt_pk_bf16_f32 v73, v84, v85
	v_pk_add_f32 v[170:171], v[170:171], v[68:69]
	v_cvt_pk_bf16_f32 v68, v74, v75
	v_cvt_pk_bf16_f32 v69, v76, v77
	s_add_i32 s84, s84, 32
	s_addk_i32 s85, 0x2000
	v_mfma_f32_32x32x16_bf16 v[18:33], v[142:145], v[66:69], v[18:33]
	s_cmp_lt_u32 s55, 5
	s_mov_b32 s55, s18
	v_mfma_f32_32x32x16_bf16 v[2:17], v[134:137], v[66:69], v[2:17]
	v_mfma_f32_32x32x16_bf16 v[18:33], v[138:141], v[70:73], v[18:33]
	v_mfma_f32_32x32x16_bf16 v[2:17], v[130:133], v[70:73], v[2:17]
	s_cbranch_scc0 .LBB0_628
	s_branch .LBB0_647
